# attention MODE0 steady loop: K-tile LDS-DMA (three tiles ahead) issued in PV gap 7, V-tile DMA left at the phase boundary
# speedup vs baseline: 1.0089x; 1.0007x over previous
.LBB0_798:
	v_add_u32_e32 v197, s10, v219
	ds_read_b64_tr_b16 v[184:185], v197 offset:24576
	ds_read_b64_tr_b16 v[186:187], v197 offset:25088
	v_mfma_f32_32x32x16_bf16 v[100:115], v[180:183], v[116:119], v[36:51]
	v_add_f32_e32 v84, v68, v69
	v_add_f32_e32 v84, v70, v84
	v_add_f32_e32 v84, v71, v84
	v_cvt_pk_bf16_f32 v148, v68, v69
	v_add_f32_e32 v84, v72, v84
	v_cvt_pk_bf16_f32 v149, v70, v71
	v_add_f32_e32 v84, v73, v84
	ds_read_b64_tr_b16 v[180:181], v197 offset:28672
	ds_read_b64_tr_b16 v[182:183], v197 offset:29184
	v_add_f32_e32 v68, v74, v84
	v_mfma_f32_32x32x16_bf16 v[84:99], v[176:179], v[116:119], v[36:51]
	v_add_f32_e32 v68, v75, v68
	v_add_f32_e32 v68, v76, v68
	v_add_f32_e32 v136, v77, v68
	v_cvt_pk_bf16_f32 v150, v72, v73
	v_cvt_pk_bf16_f32 v151, v74, v75
	ds_read_b64_tr_b16 v[68:69], v197 offset:25600
	ds_read_b64_tr_b16 v[70:71], v197 offset:26112
	v_mfma_f32_32x32x16_bf16 v[100:115], v[172:175], v[120:123], v[100:115]
	v_add_f32_e32 v72, v78, v136
	v_add_f32_e32 v72, v79, v72
	v_add_f32_e32 v72, v80, v72
	v_add_f32_e32 v136, v81, v72
	v_cvt_pk_bf16_f32 v144, v76, v77
	v_cvt_pk_bf16_f32 v145, v78, v79
	ds_read_b64_tr_b16 v[72:73], v197 offset:29696
	ds_read_b64_tr_b16 v[74:75], v197 offset:30208
	v_mfma_f32_32x32x16_bf16 v[84:99], v[168:171], v[120:123], v[84:99]
	v_add_f32_e32 v76, v82, v136
	v_add_f32_e32 v76, v83, v76
	v_add_f32_e32 v76, v52, v76
	v_add_f32_e32 v136, v53, v76
	v_cvt_pk_bf16_f32 v146, v80, v81
	v_cvt_pk_bf16_f32 v147, v82, v83
	ds_read_b64_tr_b16 v[76:77], v197 offset:26624
	ds_read_b64_tr_b16 v[78:79], v197 offset:27136
	v_mfma_f32_32x32x16_bf16 v[100:115], v[164:167], v[124:127], v[100:115]
	v_add_f32_e32 v80, v54, v136
	v_add_f32_e32 v80, v55, v80
	v_cvt_pk_bf16_f32 v140, v52, v53
	v_add_f32_e32 v80, v56, v80
	v_cvt_pk_bf16_f32 v141, v54, v55
	v_add_f32_e32 v80, v57, v80
	ds_read_b64_tr_b16 v[52:53], v197 offset:30720
	ds_read_b64_tr_b16 v[54:55], v197 offset:31232
	v_mfma_f32_32x32x16_bf16 v[84:99], v[160:163], v[124:127], v[84:99]
	v_add_f32_e32 v80, v58, v80
	v_add_f32_e32 v80, v59, v80
	v_cvt_pk_bf16_f32 v142, v56, v57
	v_add_f32_e32 v80, v60, v80
	v_cvt_pk_bf16_f32 v143, v58, v59
	v_add_f32_e32 v80, v61, v80
	ds_read_b64_tr_b16 v[56:57], v197 offset:27648
	ds_read_b64_tr_b16 v[58:59], v197 offset:28160
	v_mfma_f32_32x32x16_bf16 v[100:115], v[156:159], v[128:131], v[100:115]
	v_add_f32_e32 v80, v62, v80
	v_add_f32_e32 v80, v63, v80
	v_cvt_pk_bf16_f32 v136, v60, v61
	v_add_f32_e32 v80, v64, v80
	v_cvt_pk_bf16_f32 v137, v62, v63
	v_add_f32_e32 v80, v65, v80
	ds_read_b64_tr_b16 v[60:61], v197 offset:31744
	ds_read_b64_tr_b16 v[62:63], v197 offset:32256
	v_mfma_f32_32x32x16_bf16 v[84:99], v[152:155], v[128:131], v[84:99]
	v_add_f32_e32 v80, v66, v80
	v_cvt_pk_bf16_f32 v138, v64, v65
	v_add_f32_e32 v80, v67, v80
	v_cvt_pk_bf16_f32 v139, v66, v67
	s_add_i32 s10, s24, s47
	s_mov_b32 m0, s10
	s_nop 0
	global_load_lds_dwordx4 v203, s[98:99]
	v_add_f32_e32 v204, v220, v80
.LBB0_799:
	s_waitcnt lgkmcnt(14)
	v_mfma_f32_32x32x16_bf16 v[20:35], v[148:151], v[184:187], v[20:35]
	v_exp_f32_e32 v100, v100
	v_exp_f32_e32 v101, v101
	v_exp_f32_e32 v102, v102
	v_exp_f32_e32 v103, v103
	s_waitcnt lgkmcnt(12)
	v_mfma_f32_32x32x16_bf16 v[4:19], v[148:151], v[180:183], v[4:19]
	v_exp_f32_e32 v104, v104
	v_exp_f32_e32 v105, v105
	v_exp_f32_e32 v106, v106
	v_exp_f32_e32 v107, v107
	v_add_u32_e32 v80, s24, v218
	ds_read_b128 v[64:67], v80
	ds_read_b128 v[180:183], v80 offset:512
	s_waitcnt lgkmcnt(12)
	v_mfma_f32_32x32x16_bf16 v[20:35], v[144:147], v[68:71], v[20:35]
	v_exp_f32_e32 v108, v108
	v_exp_f32_e32 v109, v109
	v_exp_f32_e32 v110, v110
	v_exp_f32_e32 v111, v111
	ds_read_b128 v[184:187], v80 offset:2048
	ds_read_b128 v[176:179], v80 offset:2560
	s_waitcnt lgkmcnt(12)
	v_mfma_f32_32x32x16_bf16 v[4:19], v[144:147], v[72:75], v[4:19]
	v_exp_f32_e32 v112, v112
	v_exp_f32_e32 v113, v113
	v_exp_f32_e32 v114, v114
	v_exp_f32_e32 v115, v115
	ds_read_b128 v[172:175], v80 offset:4096
	ds_read_b128 v[168:171], v80 offset:4608
	s_waitcnt lgkmcnt(12)
	v_mfma_f32_32x32x16_bf16 v[20:35], v[140:143], v[76:79], v[20:35]
	v_exp_f32_e32 v84, v84
	v_exp_f32_e32 v85, v85
	v_exp_f32_e32 v86, v86
	v_exp_f32_e32 v87, v87
	ds_read_b128 v[164:167], v80 offset:6144
	ds_read_b128 v[160:163], v80 offset:6656
	s_waitcnt lgkmcnt(12)
	v_mfma_f32_32x32x16_bf16 v[4:19], v[140:143], v[52:55], v[4:19]
	v_exp_f32_e32 v88, v88
	v_exp_f32_e32 v89, v89
	v_exp_f32_e32 v90, v90
	v_exp_f32_e32 v91, v91
	s_waitcnt lgkmcnt(10)
	v_mfma_f32_32x32x16_bf16 v[20:35], v[136:139], v[56:59], v[20:35]
	s_add_i32 s10, s25, s46
	s_mov_b32 m0, s10
	s_nop 0
	global_load_lds_dwordx4 v202, s[98:99]
	v_exp_f32_e32 v92, v92
	v_exp_f32_e32 v93, v93
	v_exp_f32_e32 v94, v94
	v_exp_f32_e32 v95, v95
	s_cmp_eq_u32 s101, 32
	s_cbranch_scc1 .Lattn0_rot

.LBB0_801:
	v_add_u32_e32 v197, s25, v219
	ds_read_b64_tr_b16 v[152:153], v197 offset:24576
	ds_read_b64_tr_b16 v[154:155], v197 offset:25088
	v_mfma_f32_32x32x16_bf16 v[68:83], v[64:67], v[116:119], v[36:51]
	v_add_f32_e32 v52, v100, v101
	v_add_f32_e32 v52, v102, v52
	v_add_f32_e32 v52, v103, v52
	v_cvt_pk_bf16_f32 v148, v100, v101
	v_add_f32_e32 v52, v104, v52
	v_cvt_pk_bf16_f32 v149, v102, v103
	v_add_f32_e32 v52, v105, v52
	ds_read_b64_tr_b16 v[156:157], v197 offset:28672
	ds_read_b64_tr_b16 v[158:159], v197 offset:29184
	v_add_f32_e32 v52, v106, v52
	v_add_f32_e32 v52, v107, v52
	v_add_f32_e32 v52, v108, v52
	v_add_f32_e32 v136, v109, v52
	v_mfma_f32_32x32x16_bf16 v[52:67], v[180:183], v[116:119], v[36:51]
	v_cvt_pk_bf16_f32 v150, v104, v105
	v_cvt_pk_bf16_f32 v151, v106, v107
	ds_read_b64_tr_b16 v[100:101], v197 offset:25600
	ds_read_b64_tr_b16 v[102:103], v197 offset:26112
	v_mfma_f32_32x32x16_bf16 v[68:83], v[184:187], v[120:123], v[68:83]
	v_add_f32_e32 v104, v110, v136
	v_add_f32_e32 v104, v111, v104
	v_add_f32_e32 v104, v112, v104
	v_add_f32_e32 v136, v113, v104
	v_cvt_pk_bf16_f32 v144, v108, v109
	v_cvt_pk_bf16_f32 v145, v110, v111
	ds_read_b64_tr_b16 v[104:105], v197 offset:29696
	ds_read_b64_tr_b16 v[106:107], v197 offset:30208
	v_mfma_f32_32x32x16_bf16 v[52:67], v[176:179], v[120:123], v[52:67]
	v_add_f32_e32 v108, v114, v136
	v_add_f32_e32 v108, v115, v108
	v_add_f32_e32 v108, v84, v108
	v_add_f32_e32 v136, v85, v108
	v_cvt_pk_bf16_f32 v146, v112, v113
	v_cvt_pk_bf16_f32 v147, v114, v115
	ds_read_b64_tr_b16 v[108:109], v197 offset:26624
	ds_read_b64_tr_b16 v[110:111], v197 offset:27136
	v_mfma_f32_32x32x16_bf16 v[68:83], v[172:175], v[124:127], v[68:83]
	v_add_f32_e32 v112, v86, v136
	v_add_f32_e32 v112, v87, v112
	v_cvt_pk_bf16_f32 v140, v84, v85
	v_add_f32_e32 v112, v88, v112
	v_cvt_pk_bf16_f32 v141, v86, v87
	v_add_f32_e32 v112, v89, v112
	ds_read_b64_tr_b16 v[84:85], v197 offset:30720
	ds_read_b64_tr_b16 v[86:87], v197 offset:31232
	v_mfma_f32_32x32x16_bf16 v[52:67], v[168:171], v[124:127], v[52:67]
	v_add_f32_e32 v112, v90, v112
	v_add_f32_e32 v112, v91, v112
	v_cvt_pk_bf16_f32 v142, v88, v89
	v_add_f32_e32 v112, v92, v112
	v_cvt_pk_bf16_f32 v143, v90, v91
	v_add_f32_e32 v112, v93, v112
	ds_read_b64_tr_b16 v[88:89], v197 offset:27648
	ds_read_b64_tr_b16 v[90:91], v197 offset:28160
	v_mfma_f32_32x32x16_bf16 v[68:83], v[164:167], v[128:131], v[68:83]
	v_add_f32_e32 v112, v94, v112
	v_add_f32_e32 v112, v95, v112
	v_cvt_pk_bf16_f32 v136, v92, v93
	v_add_f32_e32 v112, v96, v112
	v_cvt_pk_bf16_f32 v137, v94, v95
	v_add_f32_e32 v112, v97, v112
	ds_read_b64_tr_b16 v[92:93], v197 offset:31744
	ds_read_b64_tr_b16 v[94:95], v197 offset:32256
	v_mfma_f32_32x32x16_bf16 v[52:67], v[160:163], v[128:131], v[52:67]
	v_add_f32_e32 v112, v98, v112
	v_cvt_pk_bf16_f32 v138, v96, v97
	v_add_f32_e32 v112, v99, v112
	v_cvt_pk_bf16_f32 v139, v98, v99
	v_add_f32_e32 v220, v204, v112
	s_add_i32 s10, s54, s47
	s_mov_b32 m0, s10
	s_nop 0
	global_load_lds_dwordx4 v199, s[98:99]
.LBB0_802:
	s_waitcnt lgkmcnt(14)
	v_mfma_f32_32x32x16_bf16 v[20:35], v[148:151], v[152:155], v[20:35]
	v_exp_f32_e32 v68, v68
	v_exp_f32_e32 v69, v69
	v_exp_f32_e32 v70, v70
	v_exp_f32_e32 v71, v71
	s_waitcnt lgkmcnt(12)
	v_mfma_f32_32x32x16_bf16 v[4:19], v[148:151], v[156:159], v[4:19]
	v_exp_f32_e32 v72, v72
	v_exp_f32_e32 v73, v73
	v_exp_f32_e32 v74, v74
	v_exp_f32_e32 v75, v75
	v_add_u32_e32 v96, s54, v218
	ds_read_b128 v[180:183], v96
	ds_read_b128 v[176:179], v96 offset:512
	s_waitcnt lgkmcnt(12)
	v_mfma_f32_32x32x16_bf16 v[20:35], v[144:147], v[100:103], v[20:35]
	v_exp_f32_e32 v76, v76
	v_exp_f32_e32 v77, v77
	v_exp_f32_e32 v78, v78
	v_exp_f32_e32 v79, v79
	ds_read_b128 v[172:175], v96 offset:2048
	ds_read_b128 v[168:171], v96 offset:2560
	s_waitcnt lgkmcnt(12)
	v_mfma_f32_32x32x16_bf16 v[4:19], v[144:147], v[104:107], v[4:19]
	v_exp_f32_e32 v80, v80
	v_exp_f32_e32 v81, v81
	v_exp_f32_e32 v82, v82
	v_exp_f32_e32 v83, v83
	ds_read_b128 v[164:167], v96 offset:4096
	ds_read_b128 v[160:163], v96 offset:4608
	s_waitcnt lgkmcnt(12)
	v_mfma_f32_32x32x16_bf16 v[20:35], v[140:143], v[108:111], v[20:35]
	v_exp_f32_e32 v52, v52
	v_exp_f32_e32 v53, v53
	v_exp_f32_e32 v54, v54
	v_exp_f32_e32 v55, v55
	ds_read_b128 v[156:159], v96 offset:6144
	ds_read_b128 v[152:155], v96 offset:6656
	s_waitcnt lgkmcnt(12)
	v_mfma_f32_32x32x16_bf16 v[4:19], v[140:143], v[84:87], v[4:19]
	v_exp_f32_e32 v56, v56
	v_exp_f32_e32 v57, v57
	v_exp_f32_e32 v58, v58
	v_exp_f32_e32 v59, v59
	s_waitcnt lgkmcnt(10)
	v_mfma_f32_32x32x16_bf16 v[20:35], v[136:139], v[88:91], v[20:35]
	s_add_i32 s10, s24, s46
	s_mov_b32 m0, s10
	s_nop 0
	global_load_lds_dwordx4 v198, s[98:99]
	v_exp_f32_e32 v60, v60
	v_exp_f32_e32 v61, v61
	v_exp_f32_e32 v62, v62
	v_exp_f32_e32 v63, v63
	v_bfe_i32 v196, v132, s101, 1
	v_bfi_b32 v246, v196, v222, v223
	s_waitcnt lgkmcnt(8)
	v_mfma_f32_32x32x16_bf16 v[4:19], v[136:139], v[92:95], v[4:19]
	v_exp_f32_e32 v64, v64
	v_exp_f32_e32 v65, v65
	v_exp_f32_e32 v66, v66
	v_exp_f32_e32 v67, v67
	v_mfma_f32_32x32x16_bf16 v[36:51], v[250:253], v[246:249], 0
	s_add_i32 s101, s101, 1
	s_add_i32 s0, s0, 2
	s_add_i32 s10, s54, 0x2000
	s_cmpk_lg_i32 s54, 0x4000
	s_cselect_b32 s42, s10, 0
	s_add_u32 s98, s98, s80
	s_addc_u32 s99, s99, s81
	s_cmp_ge_i32 s0, s1
	s_cbranch_scc1 .Lattn0_exit
	s_mov_b32 s10, s24
	s_mov_b32 s25, s54
	s_mov_b32 s24, s42
	s_branch .Lattn0_head
